# P1/P8 SwiGLU epilogue: row-scale address + 8 loads issued above the half-workgroup alignment barrier (loads in flight while the leading half waits)
# speedup vs baseline: 1.0032x; 1.0032x over previous
; __device__ __forceinline__ unsigned cvt_pk_bf16(float lo, float hi) { unsigned r; asm volatile("v_cvt_pk_bf16_f32 %0, %1, %2" : "=v"(r) : "v"(lo), "v"(hi)); return r; }
; #define PG8_BAR __builtin_amdgcn_s_barrier()
; __device__ __forceinline__ float sigmoidf_(float x) { return __builtin_amdgcn_rcpf(1.f + __builtin_amdgcn_exp2f(-x * LOG2E)); }
; template <class Epi, class Sched, bool ALIGN_EPI = false, bool SP2 = false, class Bg = BgNone>
; __device__ __forceinline__ void gemm_phase(PG8_LAS unsigned char* lds, const Gemm g, const Sched& S, const Epi& E, const int wave_sg, const Bg& bg = Bg()) {
;     ...
;         if constexpr (ALIGN_EPI) { if (wr == 0) PG8_BAR; }
;     __device__ __forceinline__ void operator()(const f32x4 (&acc)[2][2][4][2], const pg8::Unit& u, int wr, int wc, int fr, int fq) const {
;         const int row0 = u.pm * 256 + wr * 64 + fr, col0 = u.pn * 128 + wc * 32 + 8 * fq;
; #pragma unroll
;         for (int ai = 0; ai < 2; ++ai)
; #pragma unroll
;             for (int m = 0; m < 4; ++m) { const int row = row0 + ai * 128 + m * 16; const float rs = __builtin_amdgcn_rsqf(ss[row] * (1.f / DM) + EPS);
;                 float h[8];
; #pragma unroll
;                 for (int n = 0; n < 2; ++n)
; #pragma unroll
;                     for (int j = 0; j < 4; ++j) { const float g = acc[ai][0][m][n][j] * rs, up = acc[ai][1][m][n][j] * rs; h[4 * n + j] = g * sigmoidf_(g) * up; }
;                 u32x4 w; w.x = cvt_pk_bf16(h[0], h[1]); w.y = cvt_pk_bf16(h[2], h[3]); w.z = cvt_pk_bf16(h[4], h[5]); w.w = cvt_pk_bf16(h[6], h[7]);
;                 *(u32x4*)(H + (size_t)row * DFF + col0) = w; }
.LBB0_256:
	v_lshl_add_u32 v134, s44, 8, v233
	v_ashrrev_i32_e32 v135, 31, v134
	v_lshl_add_u64 v[136:137], v[134:135], 2, s[10:11]
	global_load_dword v160, v[136:137], off
	global_load_dword v161, v[136:137], off offset:64
	global_load_dword v162, v[136:137], off offset:128
	global_load_dword v163, v[136:137], off offset:192
	global_load_dword v164, v[136:137], off offset:512
	global_load_dword v165, v[136:137], off offset:576
	global_load_dword v166, v[136:137], off offset:640
	global_load_dword v167, v[136:137], off offset:704
	s_and_b64 vcc, exec, s[28:29]
	s_cbranch_vccz .LBB0_258
	s_barrier
.LBB0_258:
	v_lshl_or_b32 v138, s42, 7, v235
	v_mov_b32_e32 v143, v124
	v_mov_b32_e32 v124, v121
	v_mov_b32_e32 v140, v130
	v_mov_b32_e32 v141, v126
	v_mov_b32_e32 v126, v131
	v_mov_b32_e32 v130, v132
	v_mov_b32_e32 v131, v128
	v_mov_b32_e32 v128, v133
	v_mov_b32_e32 v132, v118
	v_mov_b32_e32 v133, v122
	v_mov_b32_e32 v122, v119
	v_mov_b32_e32 v142, v120
	v_mov_b64_e32 v[118:119], s[18:19]
	v_ashrrev_i32_e32 v139, 31, v138
	v_mad_i64_i32 v[144:145], s[0:1], v134, s74, v[118:119]
	v_lshlrev_b64 v[120:121], 1, v[138:139]
	v_lshl_add_u64 v[138:139], v[144:145], 0, v[120:121]
	s_andn2_b64 vcc, exec, s[4:5]
	s_waitcnt vmcnt(7)
	v_mov_b32_e32 v0, v160
	v_fmamk_f32 v0, v0, 0x3a800000, v237
	v_rsq_f32_e32 v0, v0
	s_nop 0
	v_pk_mul_f32 v[124:125], v[124:125], v[0:1] op_sel_hi:[1,0]
	v_pk_mul_f32 v[140:141], v[140:141], v[0:1] op_sel_hi:[1,0]
	v_pk_mul_f32 v[126:127], v[126:127], v[0:1] op_sel_hi:[1,0]
	v_pk_mul_f32 v[130:131], v[130:131], v[0:1] op_sel_hi:[1,0]
	v_pk_mul_f32 v[128:129], v[128:129], v[0:1] op_sel_hi:[1,0]
	v_pk_mul_f32 v[132:133], v[132:133], v[0:1] op_sel_hi:[1,0]
	v_pk_mul_f32 v[122:123], v[122:123], v[0:1] op_sel_hi:[1,0]
	v_pk_mul_f32 v[142:143], v[142:143], v[0:1] op_sel_hi:[1,0]
	v_mul_f32_e32 v149, 0xbfb8aa3b, v125
	v_mul_f32_e32 v0, 0xbfb8aa3b, v141
	v_mul_f32_e32 v135, 0xbfb8aa3b, v127
	v_mul_f32_e32 v144, 0xbfb8aa3b, v131
	v_mul_f32_e32 v145, 0xbfb8aa3b, v129
	v_mul_f32_e32 v146, 0xbfb8aa3b, v133
	v_mul_f32_e32 v147, 0xbfb8aa3b, v123
	v_mul_f32_e32 v148, 0xbfb8aa3b, v143
	v_exp_f32_e32 v149, v149
	v_exp_f32_e32 v0, v0
	v_exp_f32_e32 v135, v135
	v_exp_f32_e32 v144, v144
	v_exp_f32_e32 v145, v145
	v_exp_f32_e32 v146, v146
	v_exp_f32_e32 v147, v147
	v_exp_f32_e32 v148, v148
	v_add_f32_e32 v149, 1.0, v149
	v_add_f32_e32 v0, 1.0, v0
	v_add_f32_e32 v135, 1.0, v135
	v_add_f32_e32 v144, 1.0, v144
	v_add_f32_e32 v145, 1.0, v145
	v_add_f32_e32 v146, 1.0, v146
	v_add_f32_e32 v147, 1.0, v147
	v_add_f32_e32 v148, 1.0, v148
	v_rcp_f32_e32 v149, v149
	v_rcp_f32_e32 v0, v0
	v_rcp_f32_e32 v135, v135
	v_rcp_f32_e32 v144, v144
	v_rcp_f32_e32 v145, v145
	v_rcp_f32_e32 v146, v146
	v_rcp_f32_e32 v147, v147
	v_rcp_f32_e32 v148, v148
	v_mul_f32_e32 v125, v125, v149
	v_mul_f32_e32 v0, v141, v0
	v_mul_f32_e32 v127, v127, v135
	v_mul_f32_e32 v131, v131, v144
	v_mul_f32_e32 v129, v129, v145
	v_mul_f32_e32 v133, v133, v146
	v_mul_f32_e32 v123, v123, v147
	v_mul_f32_e32 v135, v143, v148
	v_mul_f32_e32 v125, v124, v125
	v_mul_f32_e32 v0, v140, v0
	v_mul_f32_e32 v126, v126, v127
	v_mul_f32_e32 v127, v130, v131
	v_mul_f32_e32 v128, v128, v129
	v_mul_f32_e32 v129, v132, v133
	v_mul_f32_e32 v130, v122, v123
	v_mul_f32_e32 v131, v142, v135
	v_cvt_pk_bf16_f32 v122, v0, v126
	v_cvt_pk_bf16_f32 v123, v127, v128
	v_cvt_pk_bf16_f32 v124, v129, v130
	v_cvt_pk_bf16_f32 v125, v131, v125
	global_store_dwordx4 v[138:139], v[122:125], off
	s_waitcnt vmcnt(7)
	v_mov_b32_e32 v0, v161
	v_fmamk_f32 v0, v0, 0x3a800000, v237
	v_rsq_f32_e32 v0, v0
	v_mov_b32_e32 v122, v114
	v_mov_b32_e32 v114, v116
	v_mov_b32_e32 v116, v102
	v_mov_b32_e32 v102, v104
	v_or_b32_e32 v104, 16, v134
	v_mov_b32_e32 v123, v110
	v_mov_b32_e32 v110, v115
	v_mov_b32_e32 v115, v112
	v_mov_b32_e32 v112, v117
	v_mov_b32_e32 v117, v106
	v_mov_b32_e32 v106, v103
	v_mov_b32_e32 v103, v108
	v_mov_b32_e32 v108, v105
	v_mad_i64_i32 v[104:105], s[0:1], v104, s74, v[118:119]
	v_lshl_add_u64 v[124:125], v[104:105], 0, v[120:121]
	v_pk_mul_f32 v[104:105], v[122:123], v[0:1] op_sel_hi:[1,0]
	v_pk_mul_f32 v[110:111], v[110:111], v[0:1] op_sel_hi:[1,0]
	v_pk_mul_f32 v[114:115], v[114:115], v[0:1] op_sel_hi:[1,0]
	v_pk_mul_f32 v[112:113], v[112:113], v[0:1] op_sel_hi:[1,0]
	v_pk_mul_f32 v[116:117], v[116:117], v[0:1] op_sel_hi:[1,0]
	v_pk_mul_f32 v[106:107], v[106:107], v[0:1] op_sel_hi:[1,0]
	v_pk_mul_f32 v[102:103], v[102:103], v[0:1] op_sel_hi:[1,0]
	v_pk_mul_f32 v[108:109], v[108:109], v[0:1] op_sel_hi:[1,0]
	v_mul_f32_e32 v0, 0xbfb8aa3b, v105
	v_mul_f32_e32 v122, 0xbfb8aa3b, v111
	v_mul_f32_e32 v123, 0xbfb8aa3b, v115
	v_mul_f32_e32 v126, 0xbfb8aa3b, v113
	v_mul_f32_e32 v127, 0xbfb8aa3b, v117
	v_mul_f32_e32 v128, 0xbfb8aa3b, v107
	v_mul_f32_e32 v129, 0xbfb8aa3b, v103
	v_mul_f32_e32 v130, 0xbfb8aa3b, v109
	v_exp_f32_e32 v0, v0
	v_exp_f32_e32 v122, v122
	v_exp_f32_e32 v123, v123
	v_exp_f32_e32 v126, v126
	v_exp_f32_e32 v127, v127
	v_exp_f32_e32 v128, v128
	v_exp_f32_e32 v129, v129
	v_exp_f32_e32 v130, v130
	v_add_f32_e32 v0, 1.0, v0
	v_add_f32_e32 v122, 1.0, v122
	v_add_f32_e32 v123, 1.0, v123
	v_add_f32_e32 v126, 1.0, v126
	v_add_f32_e32 v127, 1.0, v127
	v_add_f32_e32 v128, 1.0, v128
	v_add_f32_e32 v129, 1.0, v129
	v_add_f32_e32 v130, 1.0, v130
	v_rcp_f32_e32 v0, v0
	v_rcp_f32_e32 v122, v122
	v_rcp_f32_e32 v123, v123
	v_rcp_f32_e32 v126, v126
	v_rcp_f32_e32 v127, v127
	v_rcp_f32_e32 v128, v128
	v_rcp_f32_e32 v129, v129
	v_rcp_f32_e32 v130, v130
	v_mul_f32_e32 v0, v105, v0
	v_mul_f32_e32 v105, v111, v122
	v_mul_f32_e32 v111, v115, v123
	v_mul_f32_e32 v113, v113, v126
	v_mul_f32_e32 v115, v117, v127
	v_mul_f32_e32 v107, v107, v128
	v_mul_f32_e32 v103, v103, v129
	v_mul_f32_e32 v109, v109, v130
	v_mul_f32_e32 v0, v104, v0
	v_mul_f32_e32 v104, v110, v105
	v_mul_f32_e32 v105, v114, v111
	v_mul_f32_e32 v110, v112, v113
	v_mul_f32_e32 v111, v116, v115
	v_mul_f32_e32 v106, v106, v107
	v_mul_f32_e32 v107, v102, v103
	v_mul_f32_e32 v108, v108, v109
	v_cvt_pk_bf16_f32 v102, v0, v104
	v_cvt_pk_bf16_f32 v103, v105, v110
	v_cvt_pk_bf16_f32 v104, v111, v106
	v_cvt_pk_bf16_f32 v105, v107, v108
	global_store_dwordx4 v[124:125], v[102:105], off
	s_waitcnt vmcnt(7)
; __device__ __forceinline__ unsigned cvt_pk_bf16(float lo, float hi) { unsigned r; asm volatile("v_cvt_pk_bf16_f32 %0, %1, %2" : "=v"(r) : "v"(lo), "v"(hi)); return r; }
; __device__ __forceinline__ float sigmoidf_(float x) { return __builtin_amdgcn_rcpf(1.f + __builtin_amdgcn_exp2f(-x * LOG2E)); }
;     __device__ __forceinline__ void operator()(const f32x4 (&acc)[2][2][4][2], const pg8::Unit& u, int wr, int wc, int fr, int fq) const {
;         const int row0 = u.pm * 256 + wr * 64 + fr, col0 = u.pn * 128 + wc * 32 + 8 * fq;
; #pragma unroll
;         for (int ai = 0; ai < 2; ++ai)
; #pragma unroll
;             for (int m = 0; m < 4; ++m) { const int row = row0 + ai * 128 + m * 16; const float rs = __builtin_amdgcn_rsqf(ss[row] * (1.f / DM) + EPS);
;                 float h[8];
; #pragma unroll
;                 for (int n = 0; n < 2; ++n)
; #pragma unroll
;                     for (int j = 0; j < 4; ++j) { const float g = acc[ai][0][m][n][j] * rs, up = acc[ai][1][m][n][j] * rs; h[4 * n + j] = g * sigmoidf_(g) * up; }
;                 u32x4 w; w.x = cvt_pk_bf16(h[0], h[1]); w.y = cvt_pk_bf16(h[2], h[3]); w.z = cvt_pk_bf16(h[4], h[5]); w.w = cvt_pk_bf16(h[6], h[7]);
;                 *(u32x4*)(H + (size_t)row * DFF + col0) = w; }
	v_mov_b32_e32 v0, v162
	v_fmamk_f32 v0, v0, 0x3a800000, v237
	v_rsq_f32_e32 v0, v0
	v_mov_b32_e32 v102, v98
	v_mov_b32_e32 v98, v100
	v_mov_b32_e32 v100, v86
	v_mov_b32_e32 v86, v88
	v_or_b32_e32 v88, 32, v134
	v_mov_b32_e32 v103, v94
	v_mov_b32_e32 v94, v99
	v_mov_b32_e32 v99, v96
	v_mov_b32_e32 v96, v101
	v_mov_b32_e32 v101, v90
	v_mov_b32_e32 v90, v87
	v_mov_b32_e32 v87, v92
	v_mov_b32_e32 v92, v89
	v_mad_i64_i32 v[88:89], s[0:1], v88, s74, v[118:119]
	v_lshl_add_u64 v[104:105], v[88:89], 0, v[120:121]
	v_pk_mul_f32 v[88:89], v[102:103], v[0:1] op_sel_hi:[1,0]
	v_pk_mul_f32 v[94:95], v[94:95], v[0:1] op_sel_hi:[1,0]
	v_pk_mul_f32 v[98:99], v[98:99], v[0:1] op_sel_hi:[1,0]
	v_pk_mul_f32 v[96:97], v[96:97], v[0:1] op_sel_hi:[1,0]
	v_pk_mul_f32 v[100:101], v[100:101], v[0:1] op_sel_hi:[1,0]
	v_pk_mul_f32 v[90:91], v[90:91], v[0:1] op_sel_hi:[1,0]
	v_pk_mul_f32 v[86:87], v[86:87], v[0:1] op_sel_hi:[1,0]
	v_pk_mul_f32 v[92:93], v[92:93], v[0:1] op_sel_hi:[1,0]
	v_mul_f32_e32 v0, 0xbfb8aa3b, v89
	v_mul_f32_e32 v102, 0xbfb8aa3b, v95
	v_mul_f32_e32 v103, 0xbfb8aa3b, v99
	v_mul_f32_e32 v106, 0xbfb8aa3b, v97
	v_mul_f32_e32 v107, 0xbfb8aa3b, v101
	v_mul_f32_e32 v108, 0xbfb8aa3b, v91
	v_mul_f32_e32 v109, 0xbfb8aa3b, v87
	v_mul_f32_e32 v110, 0xbfb8aa3b, v93
	v_exp_f32_e32 v0, v0
	v_exp_f32_e32 v102, v102
	v_exp_f32_e32 v103, v103
	v_exp_f32_e32 v106, v106
	v_exp_f32_e32 v107, v107
	v_exp_f32_e32 v108, v108
	v_exp_f32_e32 v109, v109
	v_exp_f32_e32 v110, v110
	v_add_f32_e32 v0, 1.0, v0
	v_add_f32_e32 v102, 1.0, v102
	v_add_f32_e32 v103, 1.0, v103
	v_add_f32_e32 v106, 1.0, v106
	v_add_f32_e32 v107, 1.0, v107
	v_add_f32_e32 v108, 1.0, v108
	v_add_f32_e32 v109, 1.0, v109
	v_add_f32_e32 v110, 1.0, v110
	v_rcp_f32_e32 v0, v0
	v_rcp_f32_e32 v102, v102
	v_rcp_f32_e32 v103, v103
	v_rcp_f32_e32 v106, v106
	v_rcp_f32_e32 v107, v107
	v_rcp_f32_e32 v108, v108
	v_rcp_f32_e32 v109, v109
	v_rcp_f32_e32 v110, v110
	v_mul_f32_e32 v0, v89, v0
	v_mul_f32_e32 v89, v95, v102
	v_mul_f32_e32 v95, v99, v103
	v_mul_f32_e32 v97, v97, v106
	v_mul_f32_e32 v99, v101, v107
	v_mul_f32_e32 v91, v91, v108
	v_mul_f32_e32 v87, v87, v109
	v_mul_f32_e32 v93, v93, v110
	v_mul_f32_e32 v0, v88, v0
	v_mul_f32_e32 v88, v94, v89
	v_mul_f32_e32 v89, v98, v95
	v_mul_f32_e32 v94, v96, v97
	v_mul_f32_e32 v95, v100, v99
	v_mul_f32_e32 v90, v90, v91
	v_mul_f32_e32 v91, v86, v87
	v_mul_f32_e32 v92, v92, v93
	v_cvt_pk_bf16_f32 v86, v0, v88
	v_cvt_pk_bf16_f32 v87, v89, v94
	v_cvt_pk_bf16_f32 v88, v95, v90
	v_cvt_pk_bf16_f32 v89, v91, v92
	global_store_dwordx4 v[104:105], v[86:89], off
	s_waitcnt vmcnt(7)
	v_mov_b32_e32 v0, v163
	v_fmamk_f32 v0, v0, 0x3a800000, v237
	v_rsq_f32_e32 v0, v0
	v_mov_b32_e32 v86, v82
	v_mov_b32_e32 v82, v84
	v_mov_b32_e32 v84, v70
	v_mov_b32_e32 v70, v72
	v_or_b32_e32 v72, 48, v134
	v_mov_b32_e32 v87, v78
	v_mov_b32_e32 v78, v83
	v_mov_b32_e32 v83, v80
	v_mov_b32_e32 v80, v85
	v_mov_b32_e32 v85, v74
	v_mov_b32_e32 v74, v71
	v_mov_b32_e32 v71, v76
	v_mov_b32_e32 v76, v73
	v_mad_i64_i32 v[72:73], s[0:1], v72, s74, v[118:119]
	v_lshl_add_u64 v[88:89], v[72:73], 0, v[120:121]
	v_pk_mul_f32 v[72:73], v[86:87], v[0:1] op_sel_hi:[1,0]
	v_pk_mul_f32 v[78:79], v[78:79], v[0:1] op_sel_hi:[1,0]
	v_pk_mul_f32 v[82:83], v[82:83], v[0:1] op_sel_hi:[1,0]
	v_pk_mul_f32 v[80:81], v[80:81], v[0:1] op_sel_hi:[1,0]
	v_pk_mul_f32 v[84:85], v[84:85], v[0:1] op_sel_hi:[1,0]
	v_pk_mul_f32 v[74:75], v[74:75], v[0:1] op_sel_hi:[1,0]
	v_pk_mul_f32 v[70:71], v[70:71], v[0:1] op_sel_hi:[1,0]
	v_pk_mul_f32 v[76:77], v[76:77], v[0:1] op_sel_hi:[1,0]
	v_mul_f32_e32 v0, 0xbfb8aa3b, v73
	v_mul_f32_e32 v86, 0xbfb8aa3b, v79
	v_mul_f32_e32 v87, 0xbfb8aa3b, v83
	v_mul_f32_e32 v90, 0xbfb8aa3b, v81
	v_mul_f32_e32 v91, 0xbfb8aa3b, v85
	v_mul_f32_e32 v92, 0xbfb8aa3b, v75
	v_mul_f32_e32 v93, 0xbfb8aa3b, v71
	v_mul_f32_e32 v94, 0xbfb8aa3b, v77
	v_exp_f32_e32 v0, v0
	v_exp_f32_e32 v86, v86
	v_exp_f32_e32 v87, v87
	v_exp_f32_e32 v90, v90
	v_exp_f32_e32 v91, v91
	v_exp_f32_e32 v92, v92
	v_exp_f32_e32 v93, v93
	v_exp_f32_e32 v94, v94
	v_add_f32_e32 v0, 1.0, v0
	v_add_f32_e32 v86, 1.0, v86
	v_add_f32_e32 v87, 1.0, v87
	v_add_f32_e32 v90, 1.0, v90
	v_add_f32_e32 v91, 1.0, v91
	v_add_f32_e32 v92, 1.0, v92
	v_add_f32_e32 v93, 1.0, v93
	v_add_f32_e32 v94, 1.0, v94
	v_rcp_f32_e32 v0, v0
	v_rcp_f32_e32 v86, v86
	v_rcp_f32_e32 v87, v87
	v_rcp_f32_e32 v90, v90
	v_rcp_f32_e32 v91, v91
	v_rcp_f32_e32 v92, v92
	v_rcp_f32_e32 v93, v93
	v_rcp_f32_e32 v94, v94
	v_mul_f32_e32 v0, v73, v0
	v_mul_f32_e32 v73, v79, v86
	v_mul_f32_e32 v79, v83, v87
	v_mul_f32_e32 v81, v81, v90
	v_mul_f32_e32 v83, v85, v91
	v_mul_f32_e32 v75, v75, v92
	v_mul_f32_e32 v71, v71, v93
	v_mul_f32_e32 v77, v77, v94
	v_mul_f32_e32 v0, v72, v0
	v_mul_f32_e32 v72, v78, v73
	v_mul_f32_e32 v73, v82, v79
	v_mul_f32_e32 v78, v80, v81
	v_mul_f32_e32 v79, v84, v83
	v_mul_f32_e32 v74, v74, v75
	v_mul_f32_e32 v75, v70, v71
	v_mul_f32_e32 v76, v76, v77
	v_cvt_pk_bf16_f32 v70, v0, v72
	v_cvt_pk_bf16_f32 v71, v73, v78
	v_cvt_pk_bf16_f32 v72, v79, v74
	v_cvt_pk_bf16_f32 v73, v75, v76
	global_store_dwordx4 v[88:89], v[70:73], off
	s_waitcnt vmcnt(7)
; __device__ __forceinline__ unsigned cvt_pk_bf16(float lo, float hi) { unsigned r; asm volatile("v_cvt_pk_bf16_f32 %0, %1, %2" : "=v"(r) : "v"(lo), "v"(hi)); return r; }
; __device__ __forceinline__ float sigmoidf_(float x) { return __builtin_amdgcn_rcpf(1.f + __builtin_amdgcn_exp2f(-x * LOG2E)); }
;     __device__ __forceinline__ void operator()(const f32x4 (&acc)[2][2][4][2], const pg8::Unit& u, int wr, int wc, int fr, int fq) const {
;         const int row0 = u.pm * 256 + wr * 64 + fr, col0 = u.pn * 128 + wc * 32 + 8 * fq;
; #pragma unroll
;         for (int ai = 0; ai < 2; ++ai)
; #pragma unroll
;             for (int m = 0; m < 4; ++m) { const int row = row0 + ai * 128 + m * 16; const float rs = __builtin_amdgcn_rsqf(ss[row] * (1.f / DM) + EPS);
;                 float h[8];
; #pragma unroll
;                 for (int n = 0; n < 2; ++n)
; #pragma unroll
;                     for (int j = 0; j < 4; ++j) { const float g = acc[ai][0][m][n][j] * rs, up = acc[ai][1][m][n][j] * rs; h[4 * n + j] = g * sigmoidf_(g) * up; }
;                 u32x4 w; w.x = cvt_pk_bf16(h[0], h[1]); w.y = cvt_pk_bf16(h[2], h[3]); w.z = cvt_pk_bf16(h[4], h[5]); w.w = cvt_pk_bf16(h[6], h[7]);
;                 *(u32x4*)(H + (size_t)row * DFF + col0) = w; }
	v_mov_b32_e32 v0, v164
	v_fmamk_f32 v0, v0, 0x3a800000, v237
	v_rsq_f32_e32 v0, v0
	v_mov_b32_e32 v70, v66
	v_mov_b32_e32 v66, v68
	v_mov_b32_e32 v68, v54
	v_mov_b32_e32 v54, v56
	v_add_u32_e32 v56, 0x80, v134
	v_mov_b32_e32 v71, v62
	v_mov_b32_e32 v62, v67
	v_mov_b32_e32 v67, v64
	v_mov_b32_e32 v64, v69
	v_mov_b32_e32 v69, v58
	v_mov_b32_e32 v58, v55
	v_mov_b32_e32 v55, v60
	v_mov_b32_e32 v60, v57
	v_mad_i64_i32 v[56:57], s[0:1], v56, s74, v[118:119]
	v_lshl_add_u64 v[72:73], v[56:57], 0, v[120:121]
	v_pk_mul_f32 v[56:57], v[70:71], v[0:1] op_sel_hi:[1,0]
	v_pk_mul_f32 v[62:63], v[62:63], v[0:1] op_sel_hi:[1,0]
	v_pk_mul_f32 v[66:67], v[66:67], v[0:1] op_sel_hi:[1,0]
	v_pk_mul_f32 v[64:65], v[64:65], v[0:1] op_sel_hi:[1,0]
	v_pk_mul_f32 v[68:69], v[68:69], v[0:1] op_sel_hi:[1,0]
	v_pk_mul_f32 v[58:59], v[58:59], v[0:1] op_sel_hi:[1,0]
	v_pk_mul_f32 v[54:55], v[54:55], v[0:1] op_sel_hi:[1,0]
	v_pk_mul_f32 v[60:61], v[60:61], v[0:1] op_sel_hi:[1,0]
	v_mul_f32_e32 v0, 0xbfb8aa3b, v57
	v_mul_f32_e32 v70, 0xbfb8aa3b, v63
	v_mul_f32_e32 v71, 0xbfb8aa3b, v67
	v_mul_f32_e32 v74, 0xbfb8aa3b, v65
	v_mul_f32_e32 v75, 0xbfb8aa3b, v69
	v_mul_f32_e32 v76, 0xbfb8aa3b, v59
	v_mul_f32_e32 v77, 0xbfb8aa3b, v55
	v_mul_f32_e32 v78, 0xbfb8aa3b, v61
	v_exp_f32_e32 v0, v0
	v_exp_f32_e32 v70, v70
	v_exp_f32_e32 v71, v71
	v_exp_f32_e32 v74, v74
	v_exp_f32_e32 v75, v75
	v_exp_f32_e32 v76, v76
	v_exp_f32_e32 v77, v77
	v_exp_f32_e32 v78, v78
	v_add_f32_e32 v0, 1.0, v0
	v_add_f32_e32 v70, 1.0, v70
	v_add_f32_e32 v71, 1.0, v71
	v_add_f32_e32 v74, 1.0, v74
	v_add_f32_e32 v75, 1.0, v75
	v_add_f32_e32 v76, 1.0, v76
	v_add_f32_e32 v77, 1.0, v77
	v_add_f32_e32 v78, 1.0, v78
	v_rcp_f32_e32 v0, v0
	v_rcp_f32_e32 v70, v70
	v_rcp_f32_e32 v71, v71
	v_rcp_f32_e32 v74, v74
	v_rcp_f32_e32 v75, v75
	v_rcp_f32_e32 v76, v76
	v_rcp_f32_e32 v77, v77
	v_rcp_f32_e32 v78, v78
	v_mul_f32_e32 v0, v57, v0
	v_mul_f32_e32 v57, v63, v70
	v_mul_f32_e32 v63, v67, v71
	v_mul_f32_e32 v65, v65, v74
	v_mul_f32_e32 v67, v69, v75
	v_mul_f32_e32 v59, v59, v76
	v_mul_f32_e32 v55, v55, v77
	v_mul_f32_e32 v61, v61, v78
	v_mul_f32_e32 v0, v56, v0
	v_mul_f32_e32 v56, v62, v57
	v_mul_f32_e32 v57, v66, v63
	v_mul_f32_e32 v62, v64, v65
	v_mul_f32_e32 v63, v68, v67
	v_mul_f32_e32 v58, v58, v59
	v_mul_f32_e32 v59, v54, v55
	v_mul_f32_e32 v60, v60, v61
	v_cvt_pk_bf16_f32 v54, v0, v56
	v_cvt_pk_bf16_f32 v55, v57, v62
	v_cvt_pk_bf16_f32 v56, v63, v58
	v_cvt_pk_bf16_f32 v57, v59, v60
	global_store_dwordx4 v[72:73], v[54:57], off
	s_waitcnt vmcnt(7)
	v_mov_b32_e32 v0, v165
	v_fmamk_f32 v0, v0, 0x3a800000, v237
	v_rsq_f32_e32 v0, v0
	v_mov_b32_e32 v54, v50
	v_mov_b32_e32 v50, v52
	v_mov_b32_e32 v52, v38
	v_mov_b32_e32 v38, v40
	v_add_u32_e32 v40, 0x90, v134
	v_mov_b32_e32 v55, v46
	v_mov_b32_e32 v46, v51
	v_mov_b32_e32 v51, v48
	v_mov_b32_e32 v48, v53
	v_mov_b32_e32 v53, v42
	v_mov_b32_e32 v42, v39
	v_mov_b32_e32 v39, v44
	v_mov_b32_e32 v44, v41
	v_mad_i64_i32 v[40:41], s[0:1], v40, s74, v[118:119]
	v_lshl_add_u64 v[56:57], v[40:41], 0, v[120:121]
	v_pk_mul_f32 v[40:41], v[54:55], v[0:1] op_sel_hi:[1,0]
	v_pk_mul_f32 v[46:47], v[46:47], v[0:1] op_sel_hi:[1,0]
	v_pk_mul_f32 v[50:51], v[50:51], v[0:1] op_sel_hi:[1,0]
	v_pk_mul_f32 v[48:49], v[48:49], v[0:1] op_sel_hi:[1,0]
	v_pk_mul_f32 v[52:53], v[52:53], v[0:1] op_sel_hi:[1,0]
	v_pk_mul_f32 v[42:43], v[42:43], v[0:1] op_sel_hi:[1,0]
	v_pk_mul_f32 v[38:39], v[38:39], v[0:1] op_sel_hi:[1,0]
	v_pk_mul_f32 v[44:45], v[44:45], v[0:1] op_sel_hi:[1,0]
	v_mul_f32_e32 v0, 0xbfb8aa3b, v41
	v_mul_f32_e32 v54, 0xbfb8aa3b, v47
	v_mul_f32_e32 v55, 0xbfb8aa3b, v51
	v_mul_f32_e32 v58, 0xbfb8aa3b, v49
	v_mul_f32_e32 v59, 0xbfb8aa3b, v53
	v_mul_f32_e32 v60, 0xbfb8aa3b, v43
	v_mul_f32_e32 v61, 0xbfb8aa3b, v39
	v_mul_f32_e32 v62, 0xbfb8aa3b, v45
	v_exp_f32_e32 v0, v0
	v_exp_f32_e32 v54, v54
	v_exp_f32_e32 v55, v55
	v_exp_f32_e32 v58, v58
	v_exp_f32_e32 v59, v59
	v_exp_f32_e32 v60, v60
	v_exp_f32_e32 v61, v61
	v_exp_f32_e32 v62, v62
	v_add_f32_e32 v0, 1.0, v0
	v_add_f32_e32 v54, 1.0, v54
	v_add_f32_e32 v55, 1.0, v55
	v_add_f32_e32 v58, 1.0, v58
	v_add_f32_e32 v59, 1.0, v59
	v_add_f32_e32 v60, 1.0, v60
	v_add_f32_e32 v61, 1.0, v61
	v_add_f32_e32 v62, 1.0, v62
	v_rcp_f32_e32 v0, v0
	v_rcp_f32_e32 v54, v54
	v_rcp_f32_e32 v55, v55
	v_rcp_f32_e32 v58, v58
	v_rcp_f32_e32 v59, v59
	v_rcp_f32_e32 v60, v60
	v_rcp_f32_e32 v61, v61
	v_rcp_f32_e32 v62, v62
	v_mul_f32_e32 v0, v41, v0
	v_mul_f32_e32 v41, v47, v54
	v_mul_f32_e32 v47, v51, v55
	v_mul_f32_e32 v49, v49, v58
	v_mul_f32_e32 v51, v53, v59
	v_mul_f32_e32 v43, v43, v60
	v_mul_f32_e32 v39, v39, v61
	v_mul_f32_e32 v45, v45, v62
	v_mul_f32_e32 v0, v40, v0
	v_mul_f32_e32 v40, v46, v41
	v_mul_f32_e32 v41, v50, v47
	v_mul_f32_e32 v46, v48, v49
	v_mul_f32_e32 v47, v52, v51
	v_mul_f32_e32 v42, v42, v43
	v_mul_f32_e32 v43, v38, v39
	v_mul_f32_e32 v44, v44, v45
	v_cvt_pk_bf16_f32 v38, v0, v40
	v_cvt_pk_bf16_f32 v39, v41, v46
	v_cvt_pk_bf16_f32 v40, v47, v42
	v_cvt_pk_bf16_f32 v41, v43, v44
	global_store_dwordx4 v[56:57], v[38:41], off
	s_waitcnt vmcnt(7)
; __device__ __forceinline__ unsigned cvt_pk_bf16(float lo, float hi) { unsigned r; asm volatile("v_cvt_pk_bf16_f32 %0, %1, %2" : "=v"(r) : "v"(lo), "v"(hi)); return r; }
; #define PG8_BAR __builtin_amdgcn_s_barrier()
; __device__ __forceinline__ float sigmoidf_(float x) { return __builtin_amdgcn_rcpf(1.f + __builtin_amdgcn_exp2f(-x * LOG2E)); }
; template <class Epi, class Sched, bool ALIGN_EPI = false, bool SP2 = false, class Bg = BgNone>
; __device__ __forceinline__ void gemm_phase(PG8_LAS unsigned char* lds, const Gemm g, const Sched& S, const Epi& E, const int wave_sg, const Bg& bg = Bg()) {
;     ...
;         if (!has_next) break;
; #pragma unroll
;         for (int a = 0; a < 2; ++a)
; #pragma unroll
;             for (int b = 0; b < 2; ++b)
; #pragma unroll
;                 for (int m = 0; m < 4; ++m)
; #pragma unroll
;                     for (int n = 0; n < 2; ++n) acc[a][b][m][n] = (f32x4){0.f, 0.f, 0.f, 0.f};
;         cur = nxt; cA = nA; cB = nB; ++ui;
;         if constexpr (ALIGN_EPI) { if (wr == 1) PG8_BAR; }
;     __device__ __forceinline__ void operator()(const f32x4 (&acc)[2][2][4][2], const pg8::Unit& u, int wr, int wc, int fr, int fq) const {
;         const int row0 = u.pm * 256 + wr * 64 + fr, col0 = u.pn * 128 + wc * 32 + 8 * fq;
; #pragma unroll
;         for (int ai = 0; ai < 2; ++ai)
; #pragma unroll
;             for (int m = 0; m < 4; ++m) { const int row = row0 + ai * 128 + m * 16; const float rs = __builtin_amdgcn_rsqf(ss[row] * (1.f / DM) + EPS);
;                 float h[8];
; #pragma unroll
;                 for (int n = 0; n < 2; ++n)
; #pragma unroll
;                     for (int j = 0; j < 4; ++j) { const float g = acc[ai][0][m][n][j] * rs, up = acc[ai][1][m][n][j] * rs; h[4 * n + j] = g * sigmoidf_(g) * up; }
;                 u32x4 w; w.x = cvt_pk_bf16(h[0], h[1]); w.y = cvt_pk_bf16(h[2], h[3]); w.z = cvt_pk_bf16(h[4], h[5]); w.w = cvt_pk_bf16(h[6], h[7]);
;                 *(u32x4*)(H + (size_t)row * DFF + col0) = w; }
	v_mov_b32_e32 v0, v166
	v_fmamk_f32 v0, v0, 0x3a800000, v237
	v_rsq_f32_e32 v0, v0
	v_mov_b32_e32 v38, v34
	v_mov_b32_e32 v34, v36
	v_mov_b32_e32 v36, v22
	v_mov_b32_e32 v22, v24
	v_add_u32_e32 v24, 0xa0, v134
	v_mov_b32_e32 v39, v30
	v_mov_b32_e32 v30, v35
	v_mov_b32_e32 v35, v32
	v_mov_b32_e32 v32, v37
	v_mov_b32_e32 v37, v26
	v_mov_b32_e32 v26, v23
	v_mov_b32_e32 v23, v28
	v_mov_b32_e32 v28, v25
	v_mad_i64_i32 v[24:25], s[0:1], v24, s74, v[118:119]
	v_lshl_add_u64 v[40:41], v[24:25], 0, v[120:121]
	v_pk_mul_f32 v[24:25], v[38:39], v[0:1] op_sel_hi:[1,0]
	v_pk_mul_f32 v[30:31], v[30:31], v[0:1] op_sel_hi:[1,0]
	v_pk_mul_f32 v[34:35], v[34:35], v[0:1] op_sel_hi:[1,0]
	v_pk_mul_f32 v[32:33], v[32:33], v[0:1] op_sel_hi:[1,0]
	v_pk_mul_f32 v[36:37], v[36:37], v[0:1] op_sel_hi:[1,0]
	v_pk_mul_f32 v[26:27], v[26:27], v[0:1] op_sel_hi:[1,0]
	v_pk_mul_f32 v[22:23], v[22:23], v[0:1] op_sel_hi:[1,0]
	v_pk_mul_f32 v[28:29], v[28:29], v[0:1] op_sel_hi:[1,0]
	v_mul_f32_e32 v0, 0xbfb8aa3b, v25
	v_mul_f32_e32 v38, 0xbfb8aa3b, v31
	v_mul_f32_e32 v39, 0xbfb8aa3b, v35
	v_mul_f32_e32 v42, 0xbfb8aa3b, v33
	v_mul_f32_e32 v43, 0xbfb8aa3b, v37
	v_mul_f32_e32 v44, 0xbfb8aa3b, v27
	v_mul_f32_e32 v45, 0xbfb8aa3b, v23
	v_mul_f32_e32 v46, 0xbfb8aa3b, v29
	v_exp_f32_e32 v0, v0
	v_exp_f32_e32 v38, v38
	v_exp_f32_e32 v39, v39
	v_exp_f32_e32 v42, v42
	v_exp_f32_e32 v43, v43
	v_exp_f32_e32 v44, v44
	v_exp_f32_e32 v45, v45
	v_exp_f32_e32 v46, v46
	v_add_f32_e32 v0, 1.0, v0
	v_add_f32_e32 v38, 1.0, v38
	v_add_f32_e32 v39, 1.0, v39
	v_add_f32_e32 v42, 1.0, v42
	v_add_f32_e32 v43, 1.0, v43
	v_add_f32_e32 v44, 1.0, v44
	v_add_f32_e32 v45, 1.0, v45
	v_add_f32_e32 v46, 1.0, v46
	v_rcp_f32_e32 v0, v0
	v_rcp_f32_e32 v38, v38
	v_rcp_f32_e32 v39, v39
	v_rcp_f32_e32 v42, v42
	v_rcp_f32_e32 v43, v43
	v_rcp_f32_e32 v44, v44
	v_rcp_f32_e32 v45, v45
	v_rcp_f32_e32 v46, v46
	v_mul_f32_e32 v0, v25, v0
	v_mul_f32_e32 v25, v31, v38
	v_mul_f32_e32 v31, v35, v39
	v_mul_f32_e32 v33, v33, v42
	v_mul_f32_e32 v35, v37, v43
	v_mul_f32_e32 v27, v27, v44
	v_mul_f32_e32 v23, v23, v45
	v_mul_f32_e32 v29, v29, v46
	v_mul_f32_e32 v0, v24, v0
	v_mul_f32_e32 v24, v30, v25
	v_mul_f32_e32 v25, v34, v31
	v_mul_f32_e32 v30, v32, v33
	v_mul_f32_e32 v31, v36, v35
	v_mul_f32_e32 v26, v26, v27
	v_mul_f32_e32 v27, v22, v23
	v_mul_f32_e32 v28, v28, v29
	v_cvt_pk_bf16_f32 v22, v0, v24
	v_cvt_pk_bf16_f32 v23, v25, v30
	v_cvt_pk_bf16_f32 v24, v31, v26
	v_cvt_pk_bf16_f32 v25, v27, v28
	global_store_dwordx4 v[40:41], v[22:25], off
	s_waitcnt vmcnt(7)
	v_mov_b32_e32 v0, v167
	v_fmamk_f32 v0, v0, 0x3a800000, v237
	v_rsq_f32_e32 v0, v0
	v_mov_b32_e32 v22, v18
	v_mov_b32_e32 v18, v20
	v_mov_b32_e32 v20, v6
	v_mov_b32_e32 v6, v8
	v_add_u32_e32 v8, 0xb0, v134
	v_mov_b32_e32 v23, v14
	v_mov_b32_e32 v14, v19
	v_mov_b32_e32 v19, v16
	v_mov_b32_e32 v16, v21
	v_mov_b32_e32 v21, v10
	v_mov_b32_e32 v10, v7
	v_mov_b32_e32 v7, v12
	v_mov_b32_e32 v12, v9
	v_mad_i64_i32 v[8:9], s[0:1], v8, s74, v[118:119]
	v_lshl_add_u64 v[24:25], v[8:9], 0, v[120:121]
	v_pk_mul_f32 v[8:9], v[22:23], v[0:1] op_sel_hi:[1,0]
	v_pk_mul_f32 v[14:15], v[14:15], v[0:1] op_sel_hi:[1,0]
	v_pk_mul_f32 v[18:19], v[18:19], v[0:1] op_sel_hi:[1,0]
	v_pk_mul_f32 v[16:17], v[16:17], v[0:1] op_sel_hi:[1,0]
	v_pk_mul_f32 v[20:21], v[20:21], v[0:1] op_sel_hi:[1,0]
	v_pk_mul_f32 v[10:11], v[10:11], v[0:1] op_sel_hi:[1,0]
	v_pk_mul_f32 v[6:7], v[6:7], v[0:1] op_sel_hi:[1,0]
	v_pk_mul_f32 v[12:13], v[12:13], v[0:1] op_sel_hi:[1,0]
	v_mul_f32_e32 v0, 0xbfb8aa3b, v9
	v_mul_f32_e32 v22, 0xbfb8aa3b, v15
	v_mul_f32_e32 v23, 0xbfb8aa3b, v19
	v_mul_f32_e32 v26, 0xbfb8aa3b, v17
	v_mul_f32_e32 v27, 0xbfb8aa3b, v21
	v_mul_f32_e32 v28, 0xbfb8aa3b, v11
	v_mul_f32_e32 v29, 0xbfb8aa3b, v7
	v_mul_f32_e32 v30, 0xbfb8aa3b, v13
	v_exp_f32_e32 v0, v0
	v_exp_f32_e32 v22, v22
	v_exp_f32_e32 v23, v23
	v_exp_f32_e32 v26, v26
	v_exp_f32_e32 v27, v27
	v_exp_f32_e32 v28, v28
	v_exp_f32_e32 v29, v29
	v_exp_f32_e32 v30, v30
	v_add_f32_e32 v0, 1.0, v0
	v_add_f32_e32 v22, 1.0, v22
	v_add_f32_e32 v23, 1.0, v23
	v_add_f32_e32 v26, 1.0, v26
	v_add_f32_e32 v27, 1.0, v27
	v_add_f32_e32 v28, 1.0, v28
	v_add_f32_e32 v29, 1.0, v29
	v_add_f32_e32 v30, 1.0, v30
	v_rcp_f32_e32 v0, v0
	v_rcp_f32_e32 v22, v22
	v_rcp_f32_e32 v23, v23
	v_rcp_f32_e32 v26, v26
	v_rcp_f32_e32 v27, v27
	v_rcp_f32_e32 v28, v28
	v_rcp_f32_e32 v29, v29
	v_rcp_f32_e32 v30, v30
	v_mul_f32_e32 v0, v9, v0
	v_mul_f32_e32 v9, v15, v22
	v_mul_f32_e32 v15, v19, v23
	v_mul_f32_e32 v17, v17, v26
	v_mul_f32_e32 v19, v21, v27
	v_mul_f32_e32 v11, v11, v28
	v_mul_f32_e32 v7, v7, v29
	v_mul_f32_e32 v13, v13, v30
	v_mul_f32_e32 v0, v8, v0
	v_mul_f32_e32 v8, v14, v9
	v_mul_f32_e32 v9, v18, v15
	s_mov_b64 s[0:1], -1
	v_mul_f32_e32 v14, v16, v17
	v_mul_f32_e32 v15, v20, v19
	v_mul_f32_e32 v10, v10, v11
	v_mul_f32_e32 v11, v6, v7
	v_mul_f32_e32 v12, v12, v13
	v_cvt_pk_bf16_f32 v6, v0, v8
	v_cvt_pk_bf16_f32 v7, v9, v14
	v_cvt_pk_bf16_f32 v8, v15, v10
	v_cvt_pk_bf16_f32 v9, v11, v12
	global_store_dwordx4 v[24:25], v[6:9], off
	s_cbranch_vccnz .LBB0_262
	s_andn2_b64 vcc, exec, s[16:17]
	s_cbranch_vccnz .LBB0_261
	s_barrier

; __device__ __forceinline__ unsigned cvt_pk_bf16(float lo, float hi) { unsigned r; asm volatile("v_cvt_pk_bf16_f32 %0, %1, %2" : "=v"(r) : "v"(lo), "v"(hi)); return r; }
; #define PG8_BAR __builtin_amdgcn_s_barrier()
; __device__ __forceinline__ float sigmoidf_(float x) { return __builtin_amdgcn_rcpf(1.f + __builtin_amdgcn_exp2f(-x * LOG2E)); }
; template <class Epi, class Sched, bool ALIGN_EPI = false, bool SP2 = false, class Bg = BgNone>
; __device__ __forceinline__ void gemm_phase(PG8_LAS unsigned char* lds, const Gemm g, const Sched& S, const Epi& E, const int wave_sg, const Bg& bg = Bg()) {
;     ...
;         if constexpr (ALIGN_EPI) { if (wr == 0) PG8_BAR; }
;     __device__ __forceinline__ void operator()(const f32x4 (&acc)[2][2][4][2], const pg8::Unit& u, int wr, int wc, int fr, int fq) const {
;         const int row0 = u.pm * 256 + wr * 64 + fr, col0 = u.pn * 128 + wc * 32 + 8 * fq;
; #pragma unroll
;         for (int ai = 0; ai < 2; ++ai)
; #pragma unroll
;             for (int m = 0; m < 4; ++m) { const int row = row0 + ai * 128 + m * 16; const float rs = __builtin_amdgcn_rsqf(ss[row] * (1.f / DM) + EPS);
;                 float h[8];
; #pragma unroll
;                 for (int n = 0; n < 2; ++n)
; #pragma unroll
;                     for (int j = 0; j < 4; ++j) { const float g = acc[ai][0][m][n][j] * rs, up = acc[ai][1][m][n][j] * rs; h[4 * n + j] = g * sigmoidf_(g) * up; }
;                 u32x4 w; w.x = cvt_pk_bf16(h[0], h[1]); w.y = cvt_pk_bf16(h[2], h[3]); w.z = cvt_pk_bf16(h[4], h[5]); w.w = cvt_pk_bf16(h[6], h[7]);
;                 *(u32x4*)(H + (size_t)row * DFF + col0) = w; }
.LBB0_1195:
	v_lshl_add_u32 v134, s34, 8, v232
	v_ashrrev_i32_e32 v135, 31, v134
	v_lshl_add_u64 v[136:137], v[134:135], 2, s[14:15]
	global_load_dword v160, v[136:137], off
	global_load_dword v161, v[136:137], off offset:64
	global_load_dword v162, v[136:137], off offset:128
	global_load_dword v163, v[136:137], off offset:192
	global_load_dword v164, v[136:137], off offset:512
	global_load_dword v165, v[136:137], off offset:576
	global_load_dword v166, v[136:137], off offset:640
	global_load_dword v167, v[136:137], off offset:704
	s_and_b64 vcc, exec, s[18:19]
	s_cbranch_vccz .LBB0_1197
	s_barrier
.LBB0_1197:
	v_lshl_or_b32 v138, s30, 7, v234
	v_mov_b32_e32 v143, v120
	v_mov_b32_e32 v120, v125
	v_mov_b32_e32 v140, v130
	v_mov_b32_e32 v141, v126
	v_mov_b32_e32 v126, v131
	v_mov_b32_e32 v130, v132
	v_mov_b32_e32 v131, v128
	v_mov_b32_e32 v128, v133
	v_mov_b32_e32 v132, v122
	v_mov_b32_e32 v133, v118
	v_mov_b32_e32 v118, v123
	v_mov_b32_e32 v142, v124
	v_mov_b64_e32 v[122:123], s[12:13]
	v_ashrrev_i32_e32 v139, 31, v138
	v_or_b32_e32 v146, 16, v134
	v_mad_i64_i32 v[144:145], s[0:1], v134, s68, v[122:123]
	v_lshlrev_b64 v[124:125], 1, v[138:139]
	v_ashrrev_i32_e32 v147, 31, v146
	v_lshl_add_u64 v[138:139], v[144:145], 0, v[124:125]
	v_lshl_add_u64 v[144:145], v[146:147], 2, s[14:15]
	s_andn2_b64 vcc, exec, s[8:9]
	s_waitcnt vmcnt(7)
	v_mov_b32_e32 v0, v160
	v_fmamk_f32 v0, v0, 0x3a800000, v236
	v_rsq_f32_e32 v0, v0
	s_nop 0
	v_pk_mul_f32 v[120:121], v[120:121], v[0:1] op_sel_hi:[1,0]
	v_pk_mul_f32 v[140:141], v[140:141], v[0:1] op_sel_hi:[1,0]
	v_pk_mul_f32 v[126:127], v[126:127], v[0:1] op_sel_hi:[1,0]
	v_pk_mul_f32 v[130:131], v[130:131], v[0:1] op_sel_hi:[1,0]
	v_pk_mul_f32 v[128:129], v[128:129], v[0:1] op_sel_hi:[1,0]
	v_pk_mul_f32 v[132:133], v[132:133], v[0:1] op_sel_hi:[1,0]
	v_pk_mul_f32 v[118:119], v[118:119], v[0:1] op_sel_hi:[1,0]
	v_pk_mul_f32 v[142:143], v[142:143], v[0:1] op_sel_hi:[1,0]
	v_mul_f32_e32 v152, 0xbfb8aa3b, v121
	v_mul_f32_e32 v0, 0xbfb8aa3b, v141
	v_mul_f32_e32 v135, 0xbfb8aa3b, v127
	v_mul_f32_e32 v147, 0xbfb8aa3b, v131
	v_mul_f32_e32 v148, 0xbfb8aa3b, v129
	v_mul_f32_e32 v149, 0xbfb8aa3b, v133
	v_mul_f32_e32 v150, 0xbfb8aa3b, v119
	v_mul_f32_e32 v151, 0xbfb8aa3b, v143
	v_exp_f32_e32 v152, v152
	v_exp_f32_e32 v0, v0
	v_exp_f32_e32 v135, v135
	v_exp_f32_e32 v147, v147
	v_exp_f32_e32 v148, v148
	v_exp_f32_e32 v149, v149
	v_exp_f32_e32 v150, v150
	v_exp_f32_e32 v151, v151
	v_add_f32_e32 v152, 1.0, v152
	v_add_f32_e32 v0, 1.0, v0
	v_add_f32_e32 v135, 1.0, v135
	v_add_f32_e32 v147, 1.0, v147
	v_add_f32_e32 v148, 1.0, v148
	v_add_f32_e32 v149, 1.0, v149
	v_add_f32_e32 v150, 1.0, v150
	v_add_f32_e32 v151, 1.0, v151
	v_rcp_f32_e32 v152, v152
	v_rcp_f32_e32 v0, v0
	v_rcp_f32_e32 v135, v135
	v_rcp_f32_e32 v147, v147
	v_rcp_f32_e32 v148, v148
	v_rcp_f32_e32 v149, v149
	v_rcp_f32_e32 v150, v150
	v_rcp_f32_e32 v151, v151
	v_mul_f32_e32 v121, v121, v152
	v_mul_f32_e32 v0, v141, v0
	v_mul_f32_e32 v127, v127, v135
	v_mul_f32_e32 v131, v131, v147
	v_mul_f32_e32 v129, v129, v148
	v_mul_f32_e32 v133, v133, v149
	v_mul_f32_e32 v119, v119, v150
	v_mul_f32_e32 v135, v143, v151
	v_mul_f32_e32 v121, v120, v121
	v_mul_f32_e32 v0, v140, v0
	v_mul_f32_e32 v126, v126, v127
	v_mul_f32_e32 v127, v130, v131
	v_mul_f32_e32 v128, v128, v129
	v_mul_f32_e32 v129, v132, v133
	v_mul_f32_e32 v130, v118, v119
	v_mul_f32_e32 v131, v142, v135
	v_cvt_pk_bf16_f32 v118, v0, v126
	v_cvt_pk_bf16_f32 v119, v127, v128
	v_cvt_pk_bf16_f32 v120, v129, v130
	v_cvt_pk_bf16_f32 v121, v131, v121
	global_store_dwordx4 v[138:139], v[118:121], off
	s_waitcnt vmcnt(7)
	v_mov_b32_e32 v0, v161
	v_fmamk_f32 v0, v0, 0x3a800000, v236
	v_rsq_f32_e32 v0, v0
	v_mov_b32_e32 v119, v110
	v_mov_b32_e32 v110, v115
	v_mov_b32_e32 v115, v112
	v_mov_b32_e32 v112, v117
	v_mov_b32_e32 v117, v102
	v_mov_b32_e32 v102, v107
	v_mov_b32_e32 v107, v104
	v_mov_b32_e32 v104, v109
	v_mov_b32_e32 v118, v114
	v_mov_b32_e32 v114, v116
	v_mov_b32_e32 v116, v106
	v_mov_b32_e32 v106, v108
	v_or_b32_e32 v108, 32, v134
	v_pk_mul_f32 v[104:105], v[104:105], v[0:1] op_sel_hi:[1,0]
	v_ashrrev_i32_e32 v109, 31, v108
	v_pk_mul_f32 v[118:119], v[118:119], v[0:1] op_sel_hi:[1,0]
	v_pk_mul_f32 v[110:111], v[110:111], v[0:1] op_sel_hi:[1,0]
	v_pk_mul_f32 v[114:115], v[114:115], v[0:1] op_sel_hi:[1,0]
	v_pk_mul_f32 v[112:113], v[112:113], v[0:1] op_sel_hi:[1,0]
	v_pk_mul_f32 v[116:117], v[116:117], v[0:1] op_sel_hi:[1,0]
	v_pk_mul_f32 v[102:103], v[102:103], v[0:1] op_sel_hi:[1,0]
	v_pk_mul_f32 v[106:107], v[106:107], v[0:1] op_sel_hi:[1,0]
	v_mul_f32_e32 v133, 0xbfb8aa3b, v105
	v_lshl_add_u64 v[126:127], v[108:109], 2, s[14:15]
	v_mul_f32_e32 v0, 0xbfb8aa3b, v119
	v_mul_f32_e32 v109, 0xbfb8aa3b, v111
	v_mul_f32_e32 v128, 0xbfb8aa3b, v115
	v_mul_f32_e32 v129, 0xbfb8aa3b, v113
	v_mul_f32_e32 v130, 0xbfb8aa3b, v117
	v_mul_f32_e32 v131, 0xbfb8aa3b, v103
	v_mul_f32_e32 v132, 0xbfb8aa3b, v107
	v_exp_f32_e32 v133, v133
	v_exp_f32_e32 v0, v0
	v_exp_f32_e32 v109, v109
	v_exp_f32_e32 v128, v128
	v_exp_f32_e32 v129, v129
	v_exp_f32_e32 v130, v130
	v_exp_f32_e32 v131, v131
	v_exp_f32_e32 v132, v132
	v_add_f32_e32 v133, 1.0, v133
	v_add_f32_e32 v0, 1.0, v0
	v_add_f32_e32 v109, 1.0, v109
	v_add_f32_e32 v128, 1.0, v128
	v_add_f32_e32 v129, 1.0, v129
	v_add_f32_e32 v130, 1.0, v130
	v_add_f32_e32 v131, 1.0, v131
	v_add_f32_e32 v132, 1.0, v132
	v_rcp_f32_e32 v133, v133
	v_rcp_f32_e32 v0, v0
	v_rcp_f32_e32 v109, v109
	v_rcp_f32_e32 v128, v128
	v_rcp_f32_e32 v129, v129
	v_rcp_f32_e32 v130, v130
	v_rcp_f32_e32 v131, v131
	v_rcp_f32_e32 v132, v132
	v_mad_i64_i32 v[120:121], s[0:1], v146, s68, v[122:123]
	v_mul_f32_e32 v105, v105, v133
	v_lshl_add_u64 v[120:121], v[120:121], 0, v[124:125]
	v_mul_f32_e32 v0, v119, v0
	v_mul_f32_e32 v109, v111, v109
	v_mul_f32_e32 v111, v115, v128
	v_mul_f32_e32 v113, v113, v129
	v_mul_f32_e32 v115, v117, v130
	v_mul_f32_e32 v103, v103, v131
	v_mul_f32_e32 v107, v107, v132
	v_mul_f32_e32 v105, v104, v105
	v_mul_f32_e32 v0, v118, v0
	v_mul_f32_e32 v109, v110, v109
	v_mul_f32_e32 v110, v114, v111
	v_mul_f32_e32 v111, v112, v113
	v_mul_f32_e32 v112, v116, v115
	v_mul_f32_e32 v113, v102, v103
	v_mul_f32_e32 v106, v106, v107
	v_cvt_pk_bf16_f32 v102, v0, v109
	v_cvt_pk_bf16_f32 v103, v110, v111
	v_cvt_pk_bf16_f32 v104, v112, v113
	v_cvt_pk_bf16_f32 v105, v106, v105
	global_store_dwordx4 v[120:121], v[102:105], off
	s_waitcnt vmcnt(7)
; __device__ __forceinline__ unsigned cvt_pk_bf16(float lo, float hi) { unsigned r; asm volatile("v_cvt_pk_bf16_f32 %0, %1, %2" : "=v"(r) : "v"(lo), "v"(hi)); return r; }
; __device__ __forceinline__ float sigmoidf_(float x) { return __builtin_amdgcn_rcpf(1.f + __builtin_amdgcn_exp2f(-x * LOG2E)); }
;     __device__ __forceinline__ void operator()(const f32x4 (&acc)[2][2][4][2], const pg8::Unit& u, int wr, int wc, int fr, int fq) const {
;         const int row0 = u.pm * 256 + wr * 64 + fr, col0 = u.pn * 128 + wc * 32 + 8 * fq;
; #pragma unroll
;         for (int ai = 0; ai < 2; ++ai)
; #pragma unroll
;             for (int m = 0; m < 4; ++m) { const int row = row0 + ai * 128 + m * 16; const float rs = __builtin_amdgcn_rsqf(ss[row] * (1.f / DM) + EPS);
;                 float h[8];
; #pragma unroll
;                 for (int n = 0; n < 2; ++n)
; #pragma unroll
;                     for (int j = 0; j < 4; ++j) { const float g = acc[ai][0][m][n][j] * rs, up = acc[ai][1][m][n][j] * rs; h[4 * n + j] = g * sigmoidf_(g) * up; }
;                 u32x4 w; w.x = cvt_pk_bf16(h[0], h[1]); w.y = cvt_pk_bf16(h[2], h[3]); w.z = cvt_pk_bf16(h[4], h[5]); w.w = cvt_pk_bf16(h[6], h[7]);
;                 *(u32x4*)(H + (size_t)row * DFF + col0) = w; }
	v_mov_b32_e32 v0, v162
	v_fmamk_f32 v0, v0, 0x3a800000, v236
	v_rsq_f32_e32 v0, v0
	v_mov_b32_e32 v103, v94
	v_mov_b32_e32 v94, v99
	v_mov_b32_e32 v99, v96
	v_mov_b32_e32 v96, v101
	v_mov_b32_e32 v101, v86
	v_mov_b32_e32 v86, v91
	v_mov_b32_e32 v91, v88
	v_mov_b32_e32 v88, v93
	v_mov_b32_e32 v102, v98
	v_mov_b32_e32 v98, v100
	v_mov_b32_e32 v100, v90
	v_mov_b32_e32 v90, v92
	v_or_b32_e32 v92, 48, v134
	v_pk_mul_f32 v[88:89], v[88:89], v[0:1] op_sel_hi:[1,0]
	v_ashrrev_i32_e32 v93, 31, v92
	v_pk_mul_f32 v[102:103], v[102:103], v[0:1] op_sel_hi:[1,0]
	v_pk_mul_f32 v[94:95], v[94:95], v[0:1] op_sel_hi:[1,0]
	v_pk_mul_f32 v[98:99], v[98:99], v[0:1] op_sel_hi:[1,0]
	v_pk_mul_f32 v[96:97], v[96:97], v[0:1] op_sel_hi:[1,0]
	v_pk_mul_f32 v[100:101], v[100:101], v[0:1] op_sel_hi:[1,0]
	v_pk_mul_f32 v[86:87], v[86:87], v[0:1] op_sel_hi:[1,0]
	v_pk_mul_f32 v[90:91], v[90:91], v[0:1] op_sel_hi:[1,0]
	v_mul_f32_e32 v113, 0xbfb8aa3b, v89
	v_mad_i64_i32 v[104:105], s[0:1], v108, s68, v[122:123]
	v_lshl_add_u64 v[106:107], v[92:93], 2, s[14:15]
	v_mul_f32_e32 v0, 0xbfb8aa3b, v103
	v_mul_f32_e32 v93, 0xbfb8aa3b, v95
	v_mul_f32_e32 v108, 0xbfb8aa3b, v99
	v_mul_f32_e32 v109, 0xbfb8aa3b, v97
	v_mul_f32_e32 v110, 0xbfb8aa3b, v101
	v_mul_f32_e32 v111, 0xbfb8aa3b, v87
	v_mul_f32_e32 v112, 0xbfb8aa3b, v91
	v_exp_f32_e32 v113, v113
	v_exp_f32_e32 v0, v0
	v_exp_f32_e32 v93, v93
	v_exp_f32_e32 v108, v108
	v_exp_f32_e32 v109, v109
	v_exp_f32_e32 v110, v110
	v_exp_f32_e32 v111, v111
	v_exp_f32_e32 v112, v112
	v_add_f32_e32 v113, 1.0, v113
	v_add_f32_e32 v0, 1.0, v0
	v_add_f32_e32 v93, 1.0, v93
	v_add_f32_e32 v108, 1.0, v108
	v_add_f32_e32 v109, 1.0, v109
	v_add_f32_e32 v110, 1.0, v110
	v_add_f32_e32 v111, 1.0, v111
	v_add_f32_e32 v112, 1.0, v112
	v_rcp_f32_e32 v113, v113
	v_rcp_f32_e32 v0, v0
	v_rcp_f32_e32 v93, v93
	v_rcp_f32_e32 v108, v108
	v_rcp_f32_e32 v109, v109
	v_rcp_f32_e32 v110, v110
	v_rcp_f32_e32 v111, v111
	v_rcp_f32_e32 v112, v112
	v_mul_f32_e32 v89, v89, v113
	v_lshl_add_u64 v[104:105], v[104:105], 0, v[124:125]
	v_mul_f32_e32 v0, v103, v0
	v_mul_f32_e32 v93, v95, v93
	v_mul_f32_e32 v95, v99, v108
	v_mul_f32_e32 v97, v97, v109
	v_mul_f32_e32 v99, v101, v110
	v_mul_f32_e32 v87, v87, v111
	v_mul_f32_e32 v91, v91, v112
	v_mul_f32_e32 v89, v88, v89
	v_mul_f32_e32 v0, v102, v0
	v_mul_f32_e32 v93, v94, v93
	v_mul_f32_e32 v94, v98, v95
	v_mul_f32_e32 v95, v96, v97
	v_mul_f32_e32 v96, v100, v99
	v_mul_f32_e32 v97, v86, v87
	v_mul_f32_e32 v90, v90, v91
	v_cvt_pk_bf16_f32 v86, v0, v93
	v_cvt_pk_bf16_f32 v87, v94, v95
	v_cvt_pk_bf16_f32 v88, v96, v97
	v_cvt_pk_bf16_f32 v89, v90, v89
	global_store_dwordx4 v[104:105], v[86:89], off
	s_waitcnt vmcnt(7)
	v_mov_b32_e32 v0, v163
	v_fmamk_f32 v0, v0, 0x3a800000, v236
	v_rsq_f32_e32 v0, v0
	v_mov_b32_e32 v86, v82
	v_mov_b32_e32 v87, v78
	v_mov_b32_e32 v78, v83
	v_mov_b32_e32 v82, v84
	v_mov_b32_e32 v83, v80
	v_mov_b32_e32 v80, v85
	v_mov_b32_e32 v84, v70
	v_mov_b32_e32 v85, v74
	v_mov_b32_e32 v74, v71
	v_mov_b32_e32 v70, v72
	v_mov_b32_e32 v71, v76
	v_mov_b32_e32 v76, v73
	v_mad_i64_i32 v[72:73], s[0:1], v92, s68, v[122:123]
	v_lshl_add_u64 v[88:89], v[72:73], 0, v[124:125]
	v_pk_mul_f32 v[72:73], v[86:87], v[0:1] op_sel_hi:[1,0]
	v_pk_mul_f32 v[78:79], v[78:79], v[0:1] op_sel_hi:[1,0]
	v_pk_mul_f32 v[82:83], v[82:83], v[0:1] op_sel_hi:[1,0]
	v_pk_mul_f32 v[80:81], v[80:81], v[0:1] op_sel_hi:[1,0]
	v_pk_mul_f32 v[84:85], v[84:85], v[0:1] op_sel_hi:[1,0]
	v_pk_mul_f32 v[74:75], v[74:75], v[0:1] op_sel_hi:[1,0]
	v_pk_mul_f32 v[70:71], v[70:71], v[0:1] op_sel_hi:[1,0]
	v_pk_mul_f32 v[76:77], v[76:77], v[0:1] op_sel_hi:[1,0]
	v_mul_f32_e32 v0, 0xbfb8aa3b, v73
	v_mul_f32_e32 v86, 0xbfb8aa3b, v79
	v_mul_f32_e32 v87, 0xbfb8aa3b, v83
	v_mul_f32_e32 v90, 0xbfb8aa3b, v81
	v_mul_f32_e32 v91, 0xbfb8aa3b, v85
	v_mul_f32_e32 v92, 0xbfb8aa3b, v75
	v_mul_f32_e32 v93, 0xbfb8aa3b, v71
	v_mul_f32_e32 v94, 0xbfb8aa3b, v77
	v_exp_f32_e32 v0, v0
	v_exp_f32_e32 v86, v86
	v_exp_f32_e32 v87, v87
	v_exp_f32_e32 v90, v90
	v_exp_f32_e32 v91, v91
	v_exp_f32_e32 v92, v92
	v_exp_f32_e32 v93, v93
	v_exp_f32_e32 v94, v94
	v_add_f32_e32 v0, 1.0, v0
	v_add_f32_e32 v86, 1.0, v86
	v_add_f32_e32 v87, 1.0, v87
	v_add_f32_e32 v90, 1.0, v90
	v_add_f32_e32 v91, 1.0, v91
	v_add_f32_e32 v92, 1.0, v92
	v_add_f32_e32 v93, 1.0, v93
	v_add_f32_e32 v94, 1.0, v94
	v_rcp_f32_e32 v0, v0
	v_rcp_f32_e32 v86, v86
	v_rcp_f32_e32 v87, v87
	v_rcp_f32_e32 v90, v90
	v_rcp_f32_e32 v91, v91
	v_rcp_f32_e32 v92, v92
	v_rcp_f32_e32 v93, v93
	v_rcp_f32_e32 v94, v94
	v_mul_f32_e32 v0, v73, v0
	v_mul_f32_e32 v73, v79, v86
	v_mul_f32_e32 v79, v83, v87
	v_mul_f32_e32 v81, v81, v90
	v_mul_f32_e32 v83, v85, v91
	v_mul_f32_e32 v75, v75, v92
	v_mul_f32_e32 v71, v71, v93
	v_mul_f32_e32 v77, v77, v94
	v_mul_f32_e32 v0, v72, v0
	v_mul_f32_e32 v72, v78, v73
	v_mul_f32_e32 v73, v82, v79
	v_mul_f32_e32 v78, v80, v81
	v_mul_f32_e32 v79, v84, v83
	v_mul_f32_e32 v74, v74, v75
	v_mul_f32_e32 v75, v70, v71
	v_mul_f32_e32 v76, v76, v77
	v_cvt_pk_bf16_f32 v70, v0, v72
	v_cvt_pk_bf16_f32 v71, v73, v78
	v_cvt_pk_bf16_f32 v72, v79, v74
	v_cvt_pk_bf16_f32 v73, v75, v76
	global_store_dwordx4 v[88:89], v[70:73], off
	s_waitcnt vmcnt(7)
; __device__ __forceinline__ unsigned cvt_pk_bf16(float lo, float hi) { unsigned r; asm volatile("v_cvt_pk_bf16_f32 %0, %1, %2" : "=v"(r) : "v"(lo), "v"(hi)); return r; }
; __device__ __forceinline__ float sigmoidf_(float x) { return __builtin_amdgcn_rcpf(1.f + __builtin_amdgcn_exp2f(-x * LOG2E)); }
;     __device__ __forceinline__ void operator()(const f32x4 (&acc)[2][2][4][2], const pg8::Unit& u, int wr, int wc, int fr, int fq) const {
;         const int row0 = u.pm * 256 + wr * 64 + fr, col0 = u.pn * 128 + wc * 32 + 8 * fq;
; #pragma unroll
;         for (int ai = 0; ai < 2; ++ai)
; #pragma unroll
;             for (int m = 0; m < 4; ++m) { const int row = row0 + ai * 128 + m * 16; const float rs = __builtin_amdgcn_rsqf(ss[row] * (1.f / DM) + EPS);
;                 float h[8];
; #pragma unroll
;                 for (int n = 0; n < 2; ++n)
; #pragma unroll
;                     for (int j = 0; j < 4; ++j) { const float g = acc[ai][0][m][n][j] * rs, up = acc[ai][1][m][n][j] * rs; h[4 * n + j] = g * sigmoidf_(g) * up; }
;                 u32x4 w; w.x = cvt_pk_bf16(h[0], h[1]); w.y = cvt_pk_bf16(h[2], h[3]); w.z = cvt_pk_bf16(h[4], h[5]); w.w = cvt_pk_bf16(h[6], h[7]);
;                 *(u32x4*)(H + (size_t)row * DFF + col0) = w; }
	v_mov_b32_e32 v0, v164
	v_fmamk_f32 v0, v0, 0x3a800000, v236
	v_rsq_f32_e32 v0, v0
	v_mov_b32_e32 v70, v66
	v_mov_b32_e32 v66, v68
	v_mov_b32_e32 v68, v54
	v_mov_b32_e32 v54, v56
	v_add_u32_e32 v56, 0x80, v134
	v_mov_b32_e32 v71, v62
	v_mov_b32_e32 v62, v67
	v_mov_b32_e32 v67, v64
	v_mov_b32_e32 v64, v69
	v_mov_b32_e32 v69, v58
	v_mov_b32_e32 v58, v55
	v_mov_b32_e32 v55, v60
	v_mov_b32_e32 v60, v57
	v_mad_i64_i32 v[56:57], s[0:1], v56, s68, v[122:123]
	v_lshl_add_u64 v[72:73], v[56:57], 0, v[124:125]
	v_pk_mul_f32 v[56:57], v[70:71], v[0:1] op_sel_hi:[1,0]
	v_pk_mul_f32 v[62:63], v[62:63], v[0:1] op_sel_hi:[1,0]
	v_pk_mul_f32 v[66:67], v[66:67], v[0:1] op_sel_hi:[1,0]
	v_pk_mul_f32 v[64:65], v[64:65], v[0:1] op_sel_hi:[1,0]
	v_pk_mul_f32 v[68:69], v[68:69], v[0:1] op_sel_hi:[1,0]
	v_pk_mul_f32 v[58:59], v[58:59], v[0:1] op_sel_hi:[1,0]
	v_pk_mul_f32 v[54:55], v[54:55], v[0:1] op_sel_hi:[1,0]
	v_pk_mul_f32 v[60:61], v[60:61], v[0:1] op_sel_hi:[1,0]
	v_mul_f32_e32 v0, 0xbfb8aa3b, v57
	v_mul_f32_e32 v70, 0xbfb8aa3b, v63
	v_mul_f32_e32 v71, 0xbfb8aa3b, v67
	v_mul_f32_e32 v74, 0xbfb8aa3b, v65
	v_mul_f32_e32 v75, 0xbfb8aa3b, v69
	v_mul_f32_e32 v76, 0xbfb8aa3b, v59
	v_mul_f32_e32 v77, 0xbfb8aa3b, v55
	v_mul_f32_e32 v78, 0xbfb8aa3b, v61
	v_exp_f32_e32 v0, v0
	v_exp_f32_e32 v70, v70
	v_exp_f32_e32 v71, v71
	v_exp_f32_e32 v74, v74
	v_exp_f32_e32 v75, v75
	v_exp_f32_e32 v76, v76
	v_exp_f32_e32 v77, v77
	v_exp_f32_e32 v78, v78
	v_add_f32_e32 v0, 1.0, v0
	v_add_f32_e32 v70, 1.0, v70
	v_add_f32_e32 v71, 1.0, v71
	v_add_f32_e32 v74, 1.0, v74
	v_add_f32_e32 v75, 1.0, v75
	v_add_f32_e32 v76, 1.0, v76
	v_add_f32_e32 v77, 1.0, v77
	v_add_f32_e32 v78, 1.0, v78
	v_rcp_f32_e32 v0, v0
	v_rcp_f32_e32 v70, v70
	v_rcp_f32_e32 v71, v71
	v_rcp_f32_e32 v74, v74
	v_rcp_f32_e32 v75, v75
	v_rcp_f32_e32 v76, v76
	v_rcp_f32_e32 v77, v77
	v_rcp_f32_e32 v78, v78
	v_mul_f32_e32 v0, v57, v0
	v_mul_f32_e32 v57, v63, v70
	v_mul_f32_e32 v63, v67, v71
	v_mul_f32_e32 v65, v65, v74
	v_mul_f32_e32 v67, v69, v75
	v_mul_f32_e32 v59, v59, v76
	v_mul_f32_e32 v55, v55, v77
	v_mul_f32_e32 v61, v61, v78
	v_mul_f32_e32 v0, v56, v0
	v_mul_f32_e32 v56, v62, v57
	v_mul_f32_e32 v57, v66, v63
	v_mul_f32_e32 v62, v64, v65
	v_mul_f32_e32 v63, v68, v67
	v_mul_f32_e32 v58, v58, v59
	v_mul_f32_e32 v59, v54, v55
	v_mul_f32_e32 v60, v60, v61
	v_cvt_pk_bf16_f32 v54, v0, v56
	v_cvt_pk_bf16_f32 v55, v57, v62
	v_cvt_pk_bf16_f32 v56, v63, v58
	v_cvt_pk_bf16_f32 v57, v59, v60
	global_store_dwordx4 v[72:73], v[54:57], off
	s_waitcnt vmcnt(7)
	v_mov_b32_e32 v0, v165
	v_fmamk_f32 v0, v0, 0x3a800000, v236
	v_rsq_f32_e32 v0, v0
	v_mov_b32_e32 v54, v50
	v_mov_b32_e32 v50, v52
	v_mov_b32_e32 v52, v38
	v_mov_b32_e32 v38, v40
	v_add_u32_e32 v40, 0x90, v134
	v_mov_b32_e32 v55, v46
	v_mov_b32_e32 v46, v51
	v_mov_b32_e32 v51, v48
	v_mov_b32_e32 v48, v53
	v_mov_b32_e32 v53, v42
	v_mov_b32_e32 v42, v39
	v_mov_b32_e32 v39, v44
	v_mov_b32_e32 v44, v41
	v_mad_i64_i32 v[40:41], s[0:1], v40, s68, v[122:123]
	v_lshl_add_u64 v[56:57], v[40:41], 0, v[124:125]
	v_pk_mul_f32 v[40:41], v[54:55], v[0:1] op_sel_hi:[1,0]
	v_pk_mul_f32 v[46:47], v[46:47], v[0:1] op_sel_hi:[1,0]
	v_pk_mul_f32 v[50:51], v[50:51], v[0:1] op_sel_hi:[1,0]
	v_pk_mul_f32 v[48:49], v[48:49], v[0:1] op_sel_hi:[1,0]
	v_pk_mul_f32 v[52:53], v[52:53], v[0:1] op_sel_hi:[1,0]
	v_pk_mul_f32 v[42:43], v[42:43], v[0:1] op_sel_hi:[1,0]
	v_pk_mul_f32 v[38:39], v[38:39], v[0:1] op_sel_hi:[1,0]
	v_pk_mul_f32 v[44:45], v[44:45], v[0:1] op_sel_hi:[1,0]
	v_mul_f32_e32 v0, 0xbfb8aa3b, v41
	v_mul_f32_e32 v54, 0xbfb8aa3b, v47
	v_mul_f32_e32 v55, 0xbfb8aa3b, v51
	v_mul_f32_e32 v58, 0xbfb8aa3b, v49
	v_mul_f32_e32 v59, 0xbfb8aa3b, v53
	v_mul_f32_e32 v60, 0xbfb8aa3b, v43
	v_mul_f32_e32 v61, 0xbfb8aa3b, v39
	v_mul_f32_e32 v62, 0xbfb8aa3b, v45
	v_exp_f32_e32 v0, v0
	v_exp_f32_e32 v54, v54
	v_exp_f32_e32 v55, v55
	v_exp_f32_e32 v58, v58
	v_exp_f32_e32 v59, v59
	v_exp_f32_e32 v60, v60
	v_exp_f32_e32 v61, v61
	v_exp_f32_e32 v62, v62
	v_add_f32_e32 v0, 1.0, v0
	v_add_f32_e32 v54, 1.0, v54
	v_add_f32_e32 v55, 1.0, v55
	v_add_f32_e32 v58, 1.0, v58
	v_add_f32_e32 v59, 1.0, v59
	v_add_f32_e32 v60, 1.0, v60
	v_add_f32_e32 v61, 1.0, v61
	v_add_f32_e32 v62, 1.0, v62
	v_rcp_f32_e32 v0, v0
	v_rcp_f32_e32 v54, v54
	v_rcp_f32_e32 v55, v55
	v_rcp_f32_e32 v58, v58
	v_rcp_f32_e32 v59, v59
	v_rcp_f32_e32 v60, v60
	v_rcp_f32_e32 v61, v61
	v_rcp_f32_e32 v62, v62
	v_mul_f32_e32 v0, v41, v0
	v_mul_f32_e32 v41, v47, v54
	v_mul_f32_e32 v47, v51, v55
	v_mul_f32_e32 v49, v49, v58
	v_mul_f32_e32 v51, v53, v59
	v_mul_f32_e32 v43, v43, v60
	v_mul_f32_e32 v39, v39, v61
	v_mul_f32_e32 v45, v45, v62
	v_mul_f32_e32 v0, v40, v0
	v_mul_f32_e32 v40, v46, v41
	v_mul_f32_e32 v41, v50, v47
	v_mul_f32_e32 v46, v48, v49
	v_mul_f32_e32 v47, v52, v51
	v_mul_f32_e32 v42, v42, v43
	v_mul_f32_e32 v43, v38, v39
	v_mul_f32_e32 v44, v44, v45
	v_cvt_pk_bf16_f32 v38, v0, v40
	v_cvt_pk_bf16_f32 v39, v41, v46
	v_cvt_pk_bf16_f32 v40, v47, v42
	v_cvt_pk_bf16_f32 v41, v43, v44
	global_store_dwordx4 v[56:57], v[38:41], off
	s_waitcnt vmcnt(7)
; __device__ __forceinline__ unsigned cvt_pk_bf16(float lo, float hi) { unsigned r; asm volatile("v_cvt_pk_bf16_f32 %0, %1, %2" : "=v"(r) : "v"(lo), "v"(hi)); return r; }
; #define PG8_BAR __builtin_amdgcn_s_barrier()
; __device__ __forceinline__ float sigmoidf_(float x) { return __builtin_amdgcn_rcpf(1.f + __builtin_amdgcn_exp2f(-x * LOG2E)); }
; template <class Epi, class Sched, bool ALIGN_EPI = false, bool SP2 = false, class Bg = BgNone>
; __device__ __forceinline__ void gemm_phase(PG8_LAS unsigned char* lds, const Gemm g, const Sched& S, const Epi& E, const int wave_sg, const Bg& bg = Bg()) {
;     ...
;         if (!has_next) break;
; #pragma unroll
;         for (int a = 0; a < 2; ++a)
; #pragma unroll
;             for (int b = 0; b < 2; ++b)
; #pragma unroll
;                 for (int m = 0; m < 4; ++m)
; #pragma unroll
;                     for (int n = 0; n < 2; ++n) acc[a][b][m][n] = (f32x4){0.f, 0.f, 0.f, 0.f};
;         cur = nxt; cA = nA; cB = nB; ++ui;
;         if constexpr (ALIGN_EPI) { if (wr == 1) PG8_BAR; }
;     __device__ __forceinline__ void operator()(const f32x4 (&acc)[2][2][4][2], const pg8::Unit& u, int wr, int wc, int fr, int fq) const {
;         const int row0 = u.pm * 256 + wr * 64 + fr, col0 = u.pn * 128 + wc * 32 + 8 * fq;
; #pragma unroll
;         for (int ai = 0; ai < 2; ++ai)
; #pragma unroll
;             for (int m = 0; m < 4; ++m) { const int row = row0 + ai * 128 + m * 16; const float rs = __builtin_amdgcn_rsqf(ss[row] * (1.f / DM) + EPS);
;                 float h[8];
; #pragma unroll
;                 for (int n = 0; n < 2; ++n)
; #pragma unroll
;                     for (int j = 0; j < 4; ++j) { const float g = acc[ai][0][m][n][j] * rs, up = acc[ai][1][m][n][j] * rs; h[4 * n + j] = g * sigmoidf_(g) * up; }
;                 u32x4 w; w.x = cvt_pk_bf16(h[0], h[1]); w.y = cvt_pk_bf16(h[2], h[3]); w.z = cvt_pk_bf16(h[4], h[5]); w.w = cvt_pk_bf16(h[6], h[7]);
;                 *(u32x4*)(H + (size_t)row * DFF + col0) = w; }
	v_mov_b32_e32 v0, v166
	v_fmamk_f32 v0, v0, 0x3a800000, v236
	v_rsq_f32_e32 v0, v0
	v_mov_b32_e32 v38, v34
	v_mov_b32_e32 v34, v36
	v_mov_b32_e32 v36, v22
	v_mov_b32_e32 v22, v24
	v_add_u32_e32 v24, 0xa0, v134
	v_mov_b32_e32 v39, v30
	v_mov_b32_e32 v30, v35
	v_mov_b32_e32 v35, v32
	v_mov_b32_e32 v32, v37
	v_mov_b32_e32 v37, v26
	v_mov_b32_e32 v26, v23
	v_mov_b32_e32 v23, v28
	v_mov_b32_e32 v28, v25
	v_mad_i64_i32 v[24:25], s[0:1], v24, s68, v[122:123]
	v_lshl_add_u64 v[40:41], v[24:25], 0, v[124:125]
	v_pk_mul_f32 v[24:25], v[38:39], v[0:1] op_sel_hi:[1,0]
	v_pk_mul_f32 v[30:31], v[30:31], v[0:1] op_sel_hi:[1,0]
	v_pk_mul_f32 v[34:35], v[34:35], v[0:1] op_sel_hi:[1,0]
	v_pk_mul_f32 v[32:33], v[32:33], v[0:1] op_sel_hi:[1,0]
	v_pk_mul_f32 v[36:37], v[36:37], v[0:1] op_sel_hi:[1,0]
	v_pk_mul_f32 v[26:27], v[26:27], v[0:1] op_sel_hi:[1,0]
	v_pk_mul_f32 v[22:23], v[22:23], v[0:1] op_sel_hi:[1,0]
	v_pk_mul_f32 v[28:29], v[28:29], v[0:1] op_sel_hi:[1,0]
	v_mul_f32_e32 v0, 0xbfb8aa3b, v25
	v_mul_f32_e32 v38, 0xbfb8aa3b, v31
	v_mul_f32_e32 v39, 0xbfb8aa3b, v35
	v_mul_f32_e32 v42, 0xbfb8aa3b, v33
	v_mul_f32_e32 v43, 0xbfb8aa3b, v37
	v_mul_f32_e32 v44, 0xbfb8aa3b, v27
	v_mul_f32_e32 v45, 0xbfb8aa3b, v23
	v_mul_f32_e32 v46, 0xbfb8aa3b, v29
	v_exp_f32_e32 v0, v0
	v_exp_f32_e32 v38, v38
	v_exp_f32_e32 v39, v39
	v_exp_f32_e32 v42, v42
	v_exp_f32_e32 v43, v43
	v_exp_f32_e32 v44, v44
	v_exp_f32_e32 v45, v45
	v_exp_f32_e32 v46, v46
	v_add_f32_e32 v0, 1.0, v0
	v_add_f32_e32 v38, 1.0, v38
	v_add_f32_e32 v39, 1.0, v39
	v_add_f32_e32 v42, 1.0, v42
	v_add_f32_e32 v43, 1.0, v43
	v_add_f32_e32 v44, 1.0, v44
	v_add_f32_e32 v45, 1.0, v45
	v_add_f32_e32 v46, 1.0, v46
	v_rcp_f32_e32 v0, v0
	v_rcp_f32_e32 v38, v38
	v_rcp_f32_e32 v39, v39
	v_rcp_f32_e32 v42, v42
	v_rcp_f32_e32 v43, v43
	v_rcp_f32_e32 v44, v44
	v_rcp_f32_e32 v45, v45
	v_rcp_f32_e32 v46, v46
	v_mul_f32_e32 v0, v25, v0
	v_mul_f32_e32 v25, v31, v38
	v_mul_f32_e32 v31, v35, v39
	v_mul_f32_e32 v33, v33, v42
	v_mul_f32_e32 v35, v37, v43
	v_mul_f32_e32 v27, v27, v44
	v_mul_f32_e32 v23, v23, v45
	v_mul_f32_e32 v29, v29, v46
	v_mul_f32_e32 v0, v24, v0
	v_mul_f32_e32 v24, v30, v25
	v_mul_f32_e32 v25, v34, v31
	v_mul_f32_e32 v30, v32, v33
	v_mul_f32_e32 v31, v36, v35
	v_mul_f32_e32 v26, v26, v27
	v_mul_f32_e32 v27, v22, v23
	v_mul_f32_e32 v28, v28, v29
	v_cvt_pk_bf16_f32 v22, v0, v24
	v_cvt_pk_bf16_f32 v23, v25, v30
	v_cvt_pk_bf16_f32 v24, v31, v26
	v_cvt_pk_bf16_f32 v25, v27, v28
	global_store_dwordx4 v[40:41], v[22:25], off
	s_waitcnt vmcnt(7)
	v_mov_b32_e32 v0, v167
	v_fmamk_f32 v0, v0, 0x3a800000, v236
	v_rsq_f32_e32 v0, v0
	v_mov_b32_e32 v22, v18
	v_mov_b32_e32 v18, v20
	v_mov_b32_e32 v20, v6
	v_mov_b32_e32 v6, v8
	v_add_u32_e32 v8, 0xb0, v134
	v_mov_b32_e32 v23, v14
	v_mov_b32_e32 v14, v19
	v_mov_b32_e32 v19, v16
	v_mov_b32_e32 v16, v21
	v_mov_b32_e32 v21, v10
	v_mov_b32_e32 v10, v7
	v_mov_b32_e32 v7, v12
	v_mov_b32_e32 v12, v9
	v_mad_i64_i32 v[8:9], s[0:1], v8, s68, v[122:123]
	v_lshl_add_u64 v[24:25], v[8:9], 0, v[124:125]
	v_pk_mul_f32 v[8:9], v[22:23], v[0:1] op_sel_hi:[1,0]
	v_pk_mul_f32 v[14:15], v[14:15], v[0:1] op_sel_hi:[1,0]
	v_pk_mul_f32 v[18:19], v[18:19], v[0:1] op_sel_hi:[1,0]
	v_pk_mul_f32 v[16:17], v[16:17], v[0:1] op_sel_hi:[1,0]
	v_pk_mul_f32 v[20:21], v[20:21], v[0:1] op_sel_hi:[1,0]
	v_pk_mul_f32 v[10:11], v[10:11], v[0:1] op_sel_hi:[1,0]
	v_pk_mul_f32 v[6:7], v[6:7], v[0:1] op_sel_hi:[1,0]
	v_pk_mul_f32 v[12:13], v[12:13], v[0:1] op_sel_hi:[1,0]
	v_mul_f32_e32 v0, 0xbfb8aa3b, v9
	v_mul_f32_e32 v22, 0xbfb8aa3b, v15
	v_mul_f32_e32 v23, 0xbfb8aa3b, v19
	v_mul_f32_e32 v26, 0xbfb8aa3b, v17
	v_mul_f32_e32 v27, 0xbfb8aa3b, v21
	v_mul_f32_e32 v28, 0xbfb8aa3b, v11
	v_mul_f32_e32 v29, 0xbfb8aa3b, v7
	v_mul_f32_e32 v30, 0xbfb8aa3b, v13
	v_exp_f32_e32 v0, v0
	v_exp_f32_e32 v22, v22
	v_exp_f32_e32 v23, v23
	v_exp_f32_e32 v26, v26
	v_exp_f32_e32 v27, v27
	v_exp_f32_e32 v28, v28
	v_exp_f32_e32 v29, v29
	v_exp_f32_e32 v30, v30
	v_add_f32_e32 v0, 1.0, v0
	v_add_f32_e32 v22, 1.0, v22
	v_add_f32_e32 v23, 1.0, v23
	v_add_f32_e32 v26, 1.0, v26
	v_add_f32_e32 v27, 1.0, v27
	v_add_f32_e32 v28, 1.0, v28
	v_add_f32_e32 v29, 1.0, v29
	v_add_f32_e32 v30, 1.0, v30
	v_rcp_f32_e32 v0, v0
	v_rcp_f32_e32 v22, v22
	v_rcp_f32_e32 v23, v23
	v_rcp_f32_e32 v26, v26
	v_rcp_f32_e32 v27, v27
	v_rcp_f32_e32 v28, v28
	v_rcp_f32_e32 v29, v29
	v_rcp_f32_e32 v30, v30
	v_mul_f32_e32 v0, v9, v0
	v_mul_f32_e32 v9, v15, v22
	v_mul_f32_e32 v15, v19, v23
	v_mul_f32_e32 v17, v17, v26
	v_mul_f32_e32 v19, v21, v27
	v_mul_f32_e32 v11, v11, v28
	v_mul_f32_e32 v7, v7, v29
	v_mul_f32_e32 v13, v13, v30
	v_mul_f32_e32 v0, v8, v0
	v_mul_f32_e32 v8, v14, v9
	v_mul_f32_e32 v9, v18, v15
	s_mov_b64 s[0:1], -1
	v_mul_f32_e32 v14, v16, v17
	v_mul_f32_e32 v15, v20, v19
	v_mul_f32_e32 v10, v10, v11
	v_mul_f32_e32 v11, v6, v7
	v_mul_f32_e32 v12, v12, v13
	v_cvt_pk_bf16_f32 v6, v0, v8
	v_cvt_pk_bf16_f32 v7, v9, v14
	v_cvt_pk_bf16_f32 v8, v15, v10
	v_cvt_pk_bf16_f32 v9, v11, v12
	global_store_dwordx4 v[24:25], v[6:9], off
	s_cbranch_vccnz .LBB0_1201
	s_andn2_b64 vcc, exec, s[6:7]
	s_cbranch_vccnz .LBB0_1200
	s_barrier
